# alignxc
# baseline (speedup 1.0000x reference)
; __device__ __forceinline__ void convert_phase(const Params& p, char* shm) {
;     ...
;     int stride = gridDim.x * 512;
;     for (int i = blockIdx.x * 512 + threadIdx.x; i < n8; i += stride) {
;       float4 v0 = x4[(size_t)i * 2], v1 = x4[(size_t)i * 2 + 1];
;       int row = i >> 8, c = (i & 255) * 8;
;       *(uint4*)(o + tl_off(row, c, DM >> 6)) =
;           make_uint4(pack2(v0.x, v0.y), pack2(v0.z, v0.w), pack2(v1.x, v1.y), pack2(v1.z, v1.w));
;     }
.LBB0_34:
	s_or_b64 exec, exec, s[0:1]
	v_mov_b32_e32 v0, 0
	s_waitcnt lgkmcnt(0)
	s_barrier
	ds_read_b96 v[0:2], v0
	s_cmp_gt_i32 s92, 0
	v_lshl_add_u32 v160, s96, 9, v174
	s_waitcnt lgkmcnt(0)
	v_readfirstlane_b32 s0, v0
	s_nop 1
	v_writelane_b32 v244, s0, 6
	v_readfirstlane_b32 s0, v1
	s_nop 1
	v_writelane_b32 v244, s0, 7
	v_readfirstlane_b32 s0, v2
	s_nop 1
	v_writelane_b32 v244, s0, 8
	s_cselect_b64 s[0:1], -1, 0
	s_cmp_lt_i32 s93, 1
	s_cselect_b64 s[2:3], -1, 0
	s_or_b64 s[0:1], s[0:1], s[2:3]
	s_and_b64 vcc, exec, s[0:1]
	s_cbranch_vccnz .LBB0_121
	v_lshl_add_u32 v4, s96, 9, v174
	s_mov_b32 s3, 0x400000
	s_lshl_b32 s2, s94, 9
	v_cmp_gt_i32_e32 vcc, s3, v4
	s_and_saveexec_b64 s[4:5], vcc
	s_cbranch_execz .LBB0_38
	v_lshlrev_b32_e32 v0, 3, v174
	v_ashrrev_i32_e32 v5, 31, v4
	s_add_u32 s6, s90, 0xa420000
	v_lshl_add_u32 v6, s96, 12, v0
	v_lshlrev_b64 v[0:1], 5, v[4:5]
	s_addc_u32 s7, s91, 0
	v_lshl_add_u64 v[0:1], s[36:37], 0, v[0:1]
	s_ashr_i32 s3, s2, 31
	s_lshl_b32 s28, s94, 12
	v_lshl_add_u64 v[0:1], v[0:1], 0, 16
	s_lshl_b64 s[24:25], s[2:3], 5
	s_mov_b64 s[26:27], 0
	v_mov_b32_e32 v3, 0
	s_mov_b32 s3, 0x3fffff
	v_mov_b32_e32 v5, v4
	s_cmp_eq_u32 s94, 0x100
	s_cbranch_scc0 .Lxc_skip
	s_movk_i32 s98, 0x4000
	s_mov_b32 s99, 0
	v_mov_b32_e32 v71, 0
	v_lshl_add_u32 v20, s96, 11, v174
	v_ashrrev_i32_e32 v21, 31, v20
	v_lshlrev_b64 v[22:23], 5, v[20:21]
	v_lshl_add_u64 v[22:23], s[36:37], 0, v[22:23]
	v_lshl_add_u64 v[22:23], v[22:23], 0, 16
; __device__ __forceinline__ void convert_phase(const Params& p, char* shm) {
;     ...
;     int stride = gridDim.x * 512;
;     for (int i = blockIdx.x * 512 + threadIdx.x; i < n8; i += stride) {
;       float4 v0 = x4[(size_t)i * 2], v1 = x4[(size_t)i * 2 + 1];
;       int row = i >> 8, c = (i & 255) * 8;
;       *(uint4*)(o + tl_off(row, c, DM >> 6)) =
;           make_uint4(pack2(v0.x, v0.y), pack2(v0.z, v0.w), pack2(v1.x, v1.y), pack2(v1.z, v1.w));
;     }
.Lxc_loop:
	v_lshl_add_u64 v[24:25], v[22:23], 0, s[98:99]
	v_lshl_add_u64 v[26:27], v[24:25], 0, s[98:99]
	v_lshl_add_u64 v[72:73], v[26:27], 0, s[98:99]
	global_load_dwordx4 v[28:31], v[22:23], off offset:-16
	global_load_dwordx4 v[32:35], v[22:23], off
	global_load_dwordx4 v[36:39], v[24:25], off offset:-16
	global_load_dwordx4 v[40:43], v[24:25], off
	global_load_dwordx4 v[44:47], v[26:27], off offset:-16
	global_load_dwordx4 v[48:51], v[26:27], off
	global_load_dwordx4 v[52:55], v[72:73], off offset:-16
	global_load_dwordx4 v[56:59], v[72:73], off
	v_lshl_add_u64 v[22:23], s[24:25], 2, v[22:23]
	v_mov_b32_e32 v60, v20
	v_lshlrev_b32_e32 v61, 3, v60
	v_ashrrev_i32_e32 v64, 8, v60
	v_ashrrev_i32_e32 v65, 15, v60
	v_bfe_u32 v62, v61, 6, 5
	v_mad_i32_i24 v62, v65, 33, v62
	v_lshrrev_b32_e32 v65, 3, v64
	v_lshrrev_b32_e32 v66, 5, v61
	v_lshlrev_b32_e32 v67, 6, v64
	v_and_b32_e32 v65, 14, v65
	v_lshlrev_b32_e32 v68, 1, v61
	v_lshlrev_b32_e32 v64, 2, v64
	v_ashrrev_i32_e32 v63, 31, v62
	v_and_b32_e32 v67, 0x3c0, v67
	v_and_or_b32 v65, v66, 1, v65
	v_and_b32_e32 v64, 32, v64
	v_lshlrev_b64 v[62:63], 14, v[62:63]
	v_and_or_b32 v66, v68, 48, v67
	v_lshlrev_b32_e32 v65, 10, v65
	v_lshl_add_u64 v[62:63], s[6:7], 0, v[62:63]
	v_bitop3_b32 v70, v66, v65, v64 bitop3:0xde
	v_lshl_add_u64 v[62:63], v[62:63], 0, v[70:71]
	s_waitcnt vmcnt(6)
	v_cvt_pk_bf16_f32 v28, v28, v29
	v_cvt_pk_bf16_f32 v29, v30, v31
	v_cvt_pk_bf16_f32 v30, v32, v33
	v_cvt_pk_bf16_f32 v31, v34, v35
	global_store_dwordx4 v[62:63], v[28:31], off
	v_add_u32_e32 v60, 0x200, v60
	v_lshlrev_b32_e32 v61, 3, v60
	v_ashrrev_i32_e32 v64, 8, v60
	v_ashrrev_i32_e32 v65, 15, v60
	v_bfe_u32 v62, v61, 6, 5
	v_mad_i32_i24 v62, v65, 33, v62
	v_lshrrev_b32_e32 v65, 3, v64
	v_lshrrev_b32_e32 v66, 5, v61
	v_lshlrev_b32_e32 v67, 6, v64
	v_and_b32_e32 v65, 14, v65
	v_lshlrev_b32_e32 v68, 1, v61
	v_lshlrev_b32_e32 v64, 2, v64
	v_ashrrev_i32_e32 v63, 31, v62
	v_and_b32_e32 v67, 0x3c0, v67
	v_and_or_b32 v65, v66, 1, v65
	v_and_b32_e32 v64, 32, v64
	v_lshlrev_b64 v[62:63], 14, v[62:63]
	v_and_or_b32 v66, v68, 48, v67
	v_lshlrev_b32_e32 v65, 10, v65
	v_lshl_add_u64 v[62:63], s[6:7], 0, v[62:63]
	v_bitop3_b32 v70, v66, v65, v64 bitop3:0xde
	v_lshl_add_u64 v[62:63], v[62:63], 0, v[70:71]
	s_waitcnt vmcnt(5)
	v_cvt_pk_bf16_f32 v36, v36, v37
	v_cvt_pk_bf16_f32 v37, v38, v39
	v_cvt_pk_bf16_f32 v38, v40, v41
	v_cvt_pk_bf16_f32 v39, v42, v43
	global_store_dwordx4 v[62:63], v[36:39], off
	v_add_u32_e32 v60, 0x200, v60
	v_lshlrev_b32_e32 v61, 3, v60
	v_ashrrev_i32_e32 v64, 8, v60
	v_ashrrev_i32_e32 v65, 15, v60
	v_bfe_u32 v62, v61, 6, 5
	v_mad_i32_i24 v62, v65, 33, v62
	v_lshrrev_b32_e32 v65, 3, v64
	v_lshrrev_b32_e32 v66, 5, v61
	v_lshlrev_b32_e32 v67, 6, v64
	v_and_b32_e32 v65, 14, v65
	v_lshlrev_b32_e32 v68, 1, v61
	v_lshlrev_b32_e32 v64, 2, v64
	v_ashrrev_i32_e32 v63, 31, v62
	v_and_b32_e32 v67, 0x3c0, v67
	v_and_or_b32 v65, v66, 1, v65
	v_and_b32_e32 v64, 32, v64
	v_lshlrev_b64 v[62:63], 14, v[62:63]
	v_and_or_b32 v66, v68, 48, v67
	v_lshlrev_b32_e32 v65, 10, v65
	v_lshl_add_u64 v[62:63], s[6:7], 0, v[62:63]
	v_bitop3_b32 v70, v66, v65, v64 bitop3:0xde
	v_lshl_add_u64 v[62:63], v[62:63], 0, v[70:71]
	s_waitcnt vmcnt(4)
	v_cvt_pk_bf16_f32 v44, v44, v45
	v_cvt_pk_bf16_f32 v45, v46, v47
	v_cvt_pk_bf16_f32 v46, v48, v49
	v_cvt_pk_bf16_f32 v47, v50, v51
	global_store_dwordx4 v[62:63], v[44:47], off
	v_add_u32_e32 v60, 0x200, v60
	v_lshlrev_b32_e32 v61, 3, v60
	v_ashrrev_i32_e32 v64, 8, v60
	v_ashrrev_i32_e32 v65, 15, v60
	v_bfe_u32 v62, v61, 6, 5
	v_mad_i32_i24 v62, v65, 33, v62
	v_lshrrev_b32_e32 v65, 3, v64
	v_lshrrev_b32_e32 v66, 5, v61
	v_lshlrev_b32_e32 v67, 6, v64
	v_and_b32_e32 v65, 14, v65
	v_lshlrev_b32_e32 v68, 1, v61
	v_lshlrev_b32_e32 v64, 2, v64
	v_ashrrev_i32_e32 v63, 31, v62
	v_and_b32_e32 v67, 0x3c0, v67
	v_and_or_b32 v65, v66, 1, v65
	v_and_b32_e32 v64, 32, v64
	v_lshlrev_b64 v[62:63], 14, v[62:63]
	v_and_or_b32 v66, v68, 48, v67
	v_lshlrev_b32_e32 v65, 10, v65
	v_lshl_add_u64 v[62:63], s[6:7], 0, v[62:63]
	v_bitop3_b32 v70, v66, v65, v64 bitop3:0xde
	v_lshl_add_u64 v[62:63], v[62:63], 0, v[70:71]
	s_waitcnt vmcnt(3)
	v_cvt_pk_bf16_f32 v52, v52, v53
	v_cvt_pk_bf16_f32 v53, v54, v55
	v_cvt_pk_bf16_f32 v54, v56, v57
	v_cvt_pk_bf16_f32 v55, v58, v59
	global_store_dwordx4 v[62:63], v[52:55], off
	v_lshl_add_u32 v20, s2, 2, v20
	v_cmp_ge_i32_e32 vcc, s3, v20
	s_cbranch_vccnz .Lxc_loop
	s_branch .LBB0_38
.Lxc_skip:
.LBB0_37:
	global_load_dwordx4 v[8:11], v[0:1], off offset:-16
	global_load_dwordx4 v[12:15], v[0:1], off
	v_ashrrev_i32_e32 v2, 8, v5
	v_ashrrev_i32_e32 v7, 15, v5
	v_bfe_u32 v16, v6, 6, 5
	v_mad_i32_i24 v16, v7, 33, v16
	v_lshrrev_b32_e32 v7, 3, v2
	v_lshrrev_b32_e32 v18, 5, v6
	v_lshlrev_b32_e32 v20, 6, v2
	v_and_b32_e32 v7, 14, v7
	v_lshlrev_b32_e32 v19, 1, v6
	v_lshlrev_b32_e32 v2, 2, v2
	v_ashrrev_i32_e32 v17, 31, v16
	v_and_b32_e32 v20, 0x3c0, v20
	v_and_or_b32 v7, v18, 1, v7
	v_add_u32_e32 v5, s2, v5
	v_and_b32_e32 v2, 32, v2
	v_lshlrev_b64 v[16:17], 14, v[16:17]
	v_and_or_b32 v18, v19, 48, v20
	v_lshlrev_b32_e32 v7, 10, v7
	v_cmp_lt_i32_e32 vcc, s3, v5
	v_lshl_add_u64 v[16:17], s[6:7], 0, v[16:17]
	v_bitop3_b32 v2, v18, v7, v2 bitop3:0xde
	v_add_u32_e32 v6, s28, v6
	v_lshl_add_u64 v[0:1], v[0:1], 0, s[24:25]
	s_or_b64 s[26:27], vcc, s[26:27]
	v_lshl_add_u64 v[16:17], v[16:17], 0, v[2:3]
	s_waitcnt vmcnt(1)
	v_cvt_pk_bf16_f32 v8, v8, v9
	v_cvt_pk_bf16_f32 v9, v10, v11
	s_waitcnt vmcnt(0)
	v_cvt_pk_bf16_f32 v10, v12, v13
	v_cvt_pk_bf16_f32 v11, v14, v15
	global_store_dwordx4 v[16:17], v[8:11], off
	s_andn2_b64 exec, exec, s[26:27]
	s_cbranch_execnz .LBB0_37
